# attention fast path v2: hand-generated exp/sum/cvt tail; PV issued key-step-major so the second key half's exps run in the gaps of the first 8 PV MFMAs
# speedup vs baseline: 1.0167x; 1.0167x over previous
.LaF1_fast:
	s_waitcnt vmcnt(0)
	s_bitcmp1_b32 s51, 0
	s_cselect_b32 s53, 0, 0xac00
	s_setprio 1
	v_add_u32_e32 v253, s53, v171
	v_add_u32_e32 v252, s53, v181
	ds_read_b128 v[196:199], v253
	ds_read_b128 v[200:203], v253 offset:12800
	ds_read_b128 v[204:207], v253 offset:32
	ds_read_b128 v[208:211], v253 offset:12832
	ds_read_b128 v[212:215], v253 offset:64
	ds_read_b128 v[216:219], v253 offset:12864
	s_waitcnt lgkmcnt(5)
	v_mfma_f32_32x32x16_bf16 v[66:81], v[196:199], v[110:113], 0
	ds_read_b128 v[220:223], v253 offset:96
	v_lshl_add_u64 v[244:245], s[2:3], 0, v[176:177]
	s_waitcnt lgkmcnt(5)
	v_mfma_f32_32x32x16_bf16 v[82:97], v[200:203], v[110:113], 0
	ds_read_b128 v[224:227], v253 offset:12896
	v_add_co_u32_e32 v246, vcc, 0x16020000, v244
	s_waitcnt lgkmcnt(5)
	v_mfma_f32_32x32x16_bf16 v[66:81], v[204:207], v[118:121], v[66:81]
	ds_read_b128 v[228:231], v253 offset:128
	s_nop 1
	s_waitcnt lgkmcnt(5)
	v_mfma_f32_32x32x16_bf16 v[82:97], v[208:211], v[118:121], v[82:97]
	ds_read_b128 v[232:235], v253 offset:12928
	v_addc_co_u32_e32 v247, vcc, 0, v245, vcc
	s_waitcnt lgkmcnt(5)
	v_mfma_f32_32x32x16_bf16 v[66:81], v[212:215], v[122:125], v[66:81]
	ds_read_b128 v[236:239], v253 offset:160
	v_add_co_u32_e32 v244, vcc, 0x16030000, v244
	s_waitcnt lgkmcnt(5)
	v_mfma_f32_32x32x16_bf16 v[82:97], v[216:219], v[122:125], v[82:97]
	ds_read_b128 v[240:243], v253 offset:12960
	s_nop 1
	s_waitcnt lgkmcnt(5)
	v_mfma_f32_32x32x16_bf16 v[66:81], v[220:223], v[126:129], v[66:81]
	ds_read_b128 v[196:199], v253 offset:192
	v_addc_co_u32_e32 v245, vcc, 0, v245, vcc
	s_waitcnt lgkmcnt(5)
	v_mfma_f32_32x32x16_bf16 v[82:97], v[224:227], v[126:129], v[82:97]
	ds_read_b128 v[200:203], v253 offset:12992
	global_load_dwordx4 v[98:101], v[246:247], off
	s_waitcnt lgkmcnt(5)
	v_mfma_f32_32x32x16_bf16 v[66:81], v[228:231], v[130:133], v[66:81]
	ds_read_b128 v[204:207], v253 offset:224
	global_load_dwordx4 v[102:105], v[244:245], off
	s_waitcnt lgkmcnt(5)
	v_mfma_f32_32x32x16_bf16 v[82:97], v[232:235], v[130:133], v[82:97]
	ds_read_b128 v[208:211], v253 offset:13024
	v_lshl_add_u64 v[246:247], s[2:3], 0, v[178:179]
	s_waitcnt lgkmcnt(5)
	v_mfma_f32_32x32x16_bf16 v[66:81], v[236:239], v[134:137], v[66:81]
	ds_read_b128 v[212:215], v253 offset:256
	v_add_co_u32_e32 v248, vcc, 0x1a000000, v246
	s_waitcnt lgkmcnt(5)
	v_mfma_f32_32x32x16_bf16 v[82:97], v[240:243], v[134:137], v[82:97]
	ds_read_b128 v[216:219], v253 offset:13056
	v_lshl_add_u64 v[244:245], s[2:3], 0, v[174:175]
	s_waitcnt lgkmcnt(5)
	v_mfma_f32_32x32x16_bf16 v[66:81], v[196:199], v[138:141], v[66:81]
	ds_read_b128 v[220:223], v253 offset:288
	s_nop 0
	s_waitcnt lgkmcnt(5)
	v_mfma_f32_32x32x16_bf16 v[82:97], v[200:203], v[138:141], v[82:97]
	ds_read_b128 v[224:227], v253 offset:13088
	v_addc_co_u32_e32 v249, vcc, 0, v247, vcc
	s_waitcnt lgkmcnt(5)
	v_mfma_f32_32x32x16_bf16 v[66:81], v[204:207], v[142:145], v[66:81]
	ds_read_b128 v[228:231], v253 offset:320
	global_load_dwordx4 v[106:109], v[244:245], off
	s_waitcnt lgkmcnt(5)
	v_mfma_f32_32x32x16_bf16 v[82:97], v[208:211], v[142:145], v[82:97]
	ds_read_b128 v[232:235], v253 offset:13120
	global_load_dwordx4 v[114:117], v[248:249], off offset:128
	s_waitcnt lgkmcnt(5)
	v_mfma_f32_32x32x16_bf16 v[66:81], v[212:215], v[150:153], v[66:81]
	ds_read_b128 v[236:239], v253 offset:352
	v_add_co_u32_e32 v244, vcc, 0x1a400000, v246
	s_waitcnt lgkmcnt(5)
	v_mfma_f32_32x32x16_bf16 v[82:97], v[216:219], v[150:153], v[82:97]
	ds_read_b128 v[240:243], v253 offset:13152
	s_nop 1
	s_waitcnt lgkmcnt(5)
	v_mfma_f32_32x32x16_bf16 v[66:81], v[220:223], v[154:157], v[66:81]
	v_addc_co_u32_e32 v245, vcc, 0, v247, vcc
	s_waitcnt lgkmcnt(4)
	v_mfma_f32_32x32x16_bf16 v[82:97], v[224:227], v[154:157], v[82:97]
	global_load_dwordx4 v[146:149], v[244:245], off offset:128
	s_waitcnt lgkmcnt(3)
	v_mfma_f32_32x32x16_bf16 v[66:81], v[228:231], v[158:161], v[66:81]
	s_waitcnt lgkmcnt(2)
	v_mfma_f32_32x32x16_bf16 v[82:97], v[232:235], v[158:161], v[82:97]
	s_waitcnt lgkmcnt(1)
	v_mfma_f32_32x32x16_bf16 v[66:81], v[236:239], v[162:165], v[66:81]
	s_waitcnt lgkmcnt(0)
	v_mfma_f32_32x32x16_bf16 v[82:97], v[240:243], v[162:165], v[82:97]
	ds_read_b128 v[196:199], v252 offset:25600
	ds_read_b128 v[200:203], v252 offset:30208
	ds_read_b128 v[204:207], v252 offset:34816
	ds_read_b128 v[208:211], v252 offset:39424
	ds_read_b128 v[212:215], v252 offset:25632
	ds_read_b128 v[216:219], v252 offset:30240
	s_setprio 0
	s_add_i32 s54, s52, 63
	s_cmp_le_i32 s54, s47
	s_cbranch_scc1 .LaF1_1
	v_add_u32_e32 v0, s52, v168
	v_add_u32_e32 v184, 32, v0
	v_cmp_le_i32_e32 vcc, v184, v173
	v_add_u32_e32 v184, 33, v0
	s_nop 3
	v_cndmask_b32_e32 v82, v180, v82, vcc
	v_cmp_lt_i32_e32 vcc, v0, v173
	s_nop 1
	v_cndmask_b32_e32 v67, v180, v67, vcc
	v_cmp_le_i32_e32 vcc, v0, v173
	s_nop 1
	v_cndmask_b32_e32 v66, v180, v66, vcc
	v_cmp_le_i32_e32 vcc, v184, v173
	v_add_u32_e32 v184, 2, v0
	s_nop 0
	v_cndmask_b32_e32 v83, v180, v83, vcc
	v_cmp_le_i32_e32 vcc, v184, v173
	v_add_u32_e32 v184, 34, v0
	s_nop 0
	v_cndmask_b32_e32 v68, v180, v68, vcc
	v_cmp_le_i32_e32 vcc, v184, v173
	v_add_u32_e32 v184, 3, v0
	s_nop 0
	v_cndmask_b32_e32 v84, v180, v84, vcc
	v_cmp_le_i32_e32 vcc, v184, v173
	v_add_u32_e32 v184, 35, v0
	s_nop 0
	v_cndmask_b32_e32 v69, v180, v69, vcc
	v_cmp_le_i32_e32 vcc, v184, v173
	v_add_u32_e32 v184, 4, v0
	s_nop 0
	v_cndmask_b32_e32 v85, v180, v85, vcc
	v_cmp_le_i32_e32 vcc, v184, v173
	v_add_u32_e32 v184, 36, v0
	s_nop 0
	v_cndmask_b32_e32 v70, v180, v70, vcc
	v_cmp_le_i32_e32 vcc, v184, v173
	v_add_u32_e32 v184, 5, v0
	s_nop 0
	v_cndmask_b32_e32 v86, v180, v86, vcc
	v_cmp_le_i32_e32 vcc, v184, v173
	v_add_u32_e32 v184, 37, v0
	s_nop 0
	v_cndmask_b32_e32 v71, v180, v71, vcc
	v_cmp_le_i32_e32 vcc, v184, v173
	v_add_u32_e32 v184, 6, v0
	s_nop 0
	v_cndmask_b32_e32 v87, v180, v87, vcc
	v_cmp_le_i32_e32 vcc, v184, v173
	v_add_u32_e32 v184, 38, v0
	s_nop 0
	v_cndmask_b32_e32 v72, v180, v72, vcc
	v_cmp_le_i32_e32 vcc, v184, v173
	v_add_u32_e32 v184, 7, v0
	s_nop 0
	v_cndmask_b32_e32 v88, v180, v88, vcc
	v_cmp_le_i32_e32 vcc, v184, v173
	v_add_u32_e32 v184, 39, v0
	s_nop 0
	v_cndmask_b32_e32 v73, v180, v73, vcc
	v_cmp_le_i32_e32 vcc, v184, v173
	v_add_u32_e32 v184, 16, v0
	s_nop 0
	v_cndmask_b32_e32 v89, v180, v89, vcc
	v_cmp_le_i32_e32 vcc, v184, v173
	v_add_u32_e32 v184, 48, v0
	s_nop 0
	v_cndmask_b32_e32 v74, v180, v74, vcc
	v_cmp_le_i32_e32 vcc, v184, v173
	v_add_u32_e32 v184, 17, v0
	s_nop 0
	v_cndmask_b32_e32 v90, v180, v90, vcc
	v_cmp_le_i32_e32 vcc, v184, v173
	v_add_u32_e32 v184, 49, v0
	s_nop 0
	v_cndmask_b32_e32 v75, v180, v75, vcc
	v_cmp_le_i32_e32 vcc, v184, v173
	v_add_u32_e32 v184, 18, v0
	s_nop 0
	v_cndmask_b32_e32 v91, v180, v91, vcc
	v_cmp_le_i32_e32 vcc, v184, v173
	v_add_u32_e32 v184, 50, v0
	s_nop 0
	v_cndmask_b32_e32 v76, v180, v76, vcc
	v_cmp_le_i32_e32 vcc, v184, v173
	v_add_u32_e32 v184, 19, v0
	s_nop 0
	v_cndmask_b32_e32 v92, v180, v92, vcc
	v_cmp_le_i32_e32 vcc, v184, v173
	v_add_u32_e32 v184, 51, v0
	s_nop 0
	v_cndmask_b32_e32 v77, v180, v77, vcc
	v_cmp_le_i32_e32 vcc, v184, v173
	v_add_u32_e32 v184, 20, v0
	s_nop 0
	v_cndmask_b32_e32 v93, v180, v93, vcc
	v_cmp_le_i32_e32 vcc, v184, v173
	v_add_u32_e32 v184, 52, v0
	s_nop 0
	v_cndmask_b32_e32 v78, v180, v78, vcc
	v_cmp_le_i32_e32 vcc, v184, v173
	v_add_u32_e32 v184, 21, v0
	s_nop 0
	v_cndmask_b32_e32 v94, v180, v94, vcc
	v_cmp_le_i32_e32 vcc, v184, v173
	v_add_u32_e32 v184, 53, v0
	s_nop 0
	v_cndmask_b32_e32 v79, v180, v79, vcc
	v_cmp_le_i32_e32 vcc, v184, v173
	v_add_u32_e32 v184, 22, v0
	s_nop 0
	v_cndmask_b32_e32 v95, v180, v95, vcc
	v_cmp_le_i32_e32 vcc, v184, v173
	v_add_u32_e32 v184, 54, v0
	s_nop 0
	v_cndmask_b32_e32 v80, v180, v80, vcc
	v_cmp_le_i32_e32 vcc, v184, v173
	v_add_u32_e32 v184, 23, v0
	v_add_u32_e32 v0, 55, v0
	v_cndmask_b32_e32 v96, v180, v96, vcc
	v_cmp_le_i32_e32 vcc, v184, v173
	s_nop 1
	v_cndmask_b32_e32 v81, v180, v81, vcc
	v_cmp_le_i32_e32 vcc, v0, v173
	s_nop 1
	v_cndmask_b32_e32 v97, v180, v97, vcc

.LaF1_2:
	v_sub_f32_e32 v66, v66, v183
	v_sub_f32_e32 v67, v67, v183
	v_sub_f32_e32 v68, v68, v183
	v_sub_f32_e32 v69, v69, v183
	v_sub_f32_e32 v70, v70, v183
	v_sub_f32_e32 v71, v71, v183
	v_sub_f32_e32 v72, v72, v183
	v_sub_f32_e32 v73, v73, v183
	v_sub_f32_e32 v74, v74, v183
	v_sub_f32_e32 v75, v75, v183
	v_sub_f32_e32 v76, v76, v183
	v_sub_f32_e32 v77, v77, v183
	v_sub_f32_e32 v78, v78, v183
	v_sub_f32_e32 v79, v79, v183
	v_sub_f32_e32 v80, v80, v183
	v_sub_f32_e32 v81, v81, v183
	v_exp_f32_e32 v66, v66
	v_exp_f32_e32 v67, v67
	v_exp_f32_e32 v68, v68
	v_exp_f32_e32 v69, v69
	v_exp_f32_e32 v70, v70
	v_exp_f32_e32 v71, v71
	v_exp_f32_e32 v72, v72
	v_exp_f32_e32 v73, v73
	v_exp_f32_e32 v74, v74
	v_exp_f32_e32 v75, v75
	v_exp_f32_e32 v76, v76
	v_exp_f32_e32 v77, v77
	v_exp_f32_e32 v78, v78
	v_exp_f32_e32 v79, v79
	v_exp_f32_e32 v80, v80
	v_exp_f32_e32 v81, v81
	v_pk_add_f32 v[184:185], v[66:67], v[68:69]
	v_pk_add_f32 v[186:187], v[70:71], v[72:73]
	v_pk_add_f32 v[184:185], v[184:185], v[74:75]
	v_pk_add_f32 v[186:187], v[186:187], v[76:77]
	v_pk_add_f32 v[184:185], v[184:185], v[78:79]
	v_pk_add_f32 v[186:187], v[186:187], v[80:81]
	v_cvt_pk_bf16_f32 v66, v66, v67
	v_cvt_pk_bf16_f32 v67, v68, v69
	v_cvt_pk_bf16_f32 v68, v70, v71
	v_cvt_pk_bf16_f32 v69, v72, v73
	v_cvt_pk_bf16_f32 v70, v74, v75
	v_cvt_pk_bf16_f32 v71, v76, v77
	v_cvt_pk_bf16_f32 v72, v78, v79
	v_cvt_pk_bf16_f32 v73, v80, v81
	s_nop 1
	s_setprio 1
	s_waitcnt lgkmcnt(5)
	v_mfma_f32_32x32x16_bf16 v[50:65], v[196:199], v[66:69], v[50:65]
	ds_read_b128 v[220:223], v252 offset:34848
	v_sub_f32_e32 v82, v82, v183
	v_sub_f32_e32 v83, v83, v183
	v_sub_f32_e32 v84, v84, v183
	v_sub_f32_e32 v85, v85, v183
	v_sub_f32_e32 v86, v86, v183
	v_sub_f32_e32 v87, v87, v183
	v_sub_f32_e32 v88, v88, v183
	s_waitcnt lgkmcnt(5)
	v_mfma_f32_32x32x16_bf16 v[34:49], v[200:203], v[66:69], v[34:49]
	ds_read_b128 v[224:227], v252 offset:39456
	v_sub_f32_e32 v89, v89, v183
	v_sub_f32_e32 v90, v90, v183
	v_sub_f32_e32 v91, v91, v183
	v_sub_f32_e32 v92, v92, v183
	v_sub_f32_e32 v93, v93, v183
	v_sub_f32_e32 v94, v94, v183
	v_sub_f32_e32 v95, v95, v183
	s_waitcnt lgkmcnt(5)
	v_mfma_f32_32x32x16_bf16 v[18:33], v[204:207], v[66:69], v[18:33]
	ds_read_b128 v[228:231], v252 offset:25664
	v_sub_f32_e32 v96, v96, v183
	v_sub_f32_e32 v97, v97, v183
	v_exp_f32_e32 v82, v82
	v_exp_f32_e32 v83, v83
	v_exp_f32_e32 v84, v84
	v_exp_f32_e32 v85, v85
	v_exp_f32_e32 v86, v86
	s_waitcnt lgkmcnt(5)
	v_mfma_f32_32x32x16_bf16 v[2:17], v[208:211], v[66:69], v[2:17]
	ds_read_b128 v[232:235], v252 offset:30272
	v_exp_f32_e32 v87, v87
	v_exp_f32_e32 v88, v88
	v_exp_f32_e32 v89, v89
	v_exp_f32_e32 v90, v90
	v_exp_f32_e32 v91, v91
	v_exp_f32_e32 v92, v92
	v_exp_f32_e32 v93, v93
	s_waitcnt lgkmcnt(5)
	v_mfma_f32_32x32x16_bf16 v[50:65], v[212:215], v[70:73], v[50:65]
	ds_read_b128 v[236:239], v252 offset:34880
	v_exp_f32_e32 v94, v94
	v_exp_f32_e32 v95, v95
	v_exp_f32_e32 v96, v96
	v_exp_f32_e32 v97, v97
	v_pk_add_f32 v[184:185], v[184:185], v[82:83]
	v_pk_add_f32 v[186:187], v[186:187], v[84:85]
	v_pk_add_f32 v[184:185], v[184:185], v[86:87]
	s_waitcnt lgkmcnt(5)
	v_mfma_f32_32x32x16_bf16 v[34:49], v[216:219], v[70:73], v[34:49]
	ds_read_b128 v[240:243], v252 offset:39488
	v_pk_add_f32 v[186:187], v[186:187], v[88:89]
	v_pk_add_f32 v[184:185], v[184:185], v[90:91]
	v_pk_add_f32 v[186:187], v[186:187], v[92:93]
	v_pk_add_f32 v[184:185], v[184:185], v[94:95]
	v_pk_add_f32 v[186:187], v[186:187], v[96:97]
	v_pk_add_f32 v[184:185], v[184:185], v[186:187]
	v_cvt_pk_bf16_f32 v74, v82, v83
	s_waitcnt lgkmcnt(5)
	v_mfma_f32_32x32x16_bf16 v[18:33], v[220:223], v[70:73], v[18:33]
	ds_read_b128 v[196:199], v252 offset:25696
	v_cvt_pk_bf16_f32 v75, v84, v85
	v_cvt_pk_bf16_f32 v76, v86, v87
	v_cvt_pk_bf16_f32 v77, v88, v89
	v_cvt_pk_bf16_f32 v78, v90, v91
	v_cvt_pk_bf16_f32 v79, v92, v93
	v_cvt_pk_bf16_f32 v80, v94, v95
	v_cvt_pk_bf16_f32 v81, v96, v97
	s_waitcnt lgkmcnt(5)
	v_mfma_f32_32x32x16_bf16 v[2:17], v[224:227], v[70:73], v[2:17]
	ds_read_b128 v[200:203], v252 offset:30304
	v_add_f32_e32 v184, v184, v185
	v_add_f32_e32 v182, v182, v184
	s_waitcnt lgkmcnt(5)
	v_mfma_f32_32x32x16_bf16 v[50:65], v[228:231], v[74:77], v[50:65]
	ds_read_b128 v[204:207], v252 offset:34912
	s_bitcmp1_b32 s51, 0
	s_cselect_b32 s99, 0xac00, 0
	s_waitcnt lgkmcnt(5)
	v_mfma_f32_32x32x16_bf16 v[34:49], v[232:235], v[74:77], v[34:49]
	ds_read_b128 v[208:211], v252 offset:39520
	s_add_i32 s99, s99, 0
	v_add_u32_e32 v250, s99, v170
	s_waitcnt lgkmcnt(5)
	v_mfma_f32_32x32x16_bf16 v[18:33], v[236:239], v[74:77], v[18:33]
	s_waitcnt vmcnt(4)
	ds_write_b128 v250, v[98:101]
	s_waitcnt lgkmcnt(5)
	v_mfma_f32_32x32x16_bf16 v[2:17], v[240:243], v[74:77], v[2:17]
	s_waitcnt vmcnt(3)
	ds_write_b128 v250, v[102:105] offset:12800
	s_waitcnt lgkmcnt(5)
	v_mfma_f32_32x32x16_bf16 v[50:65], v[196:199], v[78:81], v[50:65]
	v_add_u32_e32 v250, s99, v172
	s_waitcnt vmcnt(2)
	s_waitcnt lgkmcnt(4)
	v_mfma_f32_32x32x16_bf16 v[34:49], v[200:203], v[78:81], v[34:49]
	ds_write_b128 v250, v[106:109] offset:256
	v_add_u32_e32 v250, s99, v169
	s_waitcnt lgkmcnt(4)
	v_mfma_f32_32x32x16_bf16 v[18:33], v[204:207], v[78:81], v[18:33]
	s_waitcnt vmcnt(1)
	ds_write_b128 v250, v[114:117] offset:25600
	s_waitcnt lgkmcnt(4)
	v_mfma_f32_32x32x16_bf16 v[2:17], v[208:211], v[78:81], v[2:17]
	s_waitcnt vmcnt(0)
	ds_write_b128 v250, v[146:149] offset:34816
	s_setprio 0
	s_branch .LBB0_1478

.LaF2_fast:
	s_waitcnt vmcnt(0)
	s_bitcmp1_b32 s36, 0
	s_cselect_b32 s4, 0, 0xac00
	s_setprio 1
	v_add_u32_e32 v253, s4, v171
	v_add_u32_e32 v252, s4, v181
	ds_read_b128 v[196:199], v253
	ds_read_b128 v[200:203], v253 offset:12800
	ds_read_b128 v[204:207], v253 offset:32
	ds_read_b128 v[208:211], v253 offset:12832
	ds_read_b128 v[212:215], v253 offset:64
	ds_read_b128 v[216:219], v253 offset:12864
	s_waitcnt lgkmcnt(5)
	v_mfma_f32_32x32x16_bf16 v[66:81], v[196:199], v[110:113], 0
	ds_read_b128 v[220:223], v253 offset:96
	v_lshl_add_u64 v[244:245], s[2:3], 0, v[176:177]
	s_waitcnt lgkmcnt(5)
	v_mfma_f32_32x32x16_bf16 v[82:97], v[200:203], v[110:113], 0
	ds_read_b128 v[224:227], v253 offset:12896
	v_add_co_u32_e32 v246, vcc, 0x16020000, v244
	s_waitcnt lgkmcnt(5)
	v_mfma_f32_32x32x16_bf16 v[66:81], v[204:207], v[114:117], v[66:81]
	ds_read_b128 v[228:231], v253 offset:128
	s_nop 1
	s_waitcnt lgkmcnt(5)
	v_mfma_f32_32x32x16_bf16 v[82:97], v[208:211], v[114:117], v[82:97]
	ds_read_b128 v[232:235], v253 offset:12928
	v_addc_co_u32_e32 v247, vcc, 0, v245, vcc
	s_waitcnt lgkmcnt(5)
	v_mfma_f32_32x32x16_bf16 v[66:81], v[212:215], v[118:121], v[66:81]
	ds_read_b128 v[236:239], v253 offset:160
	v_add_co_u32_e32 v244, vcc, 0x16030000, v244
	s_waitcnt lgkmcnt(5)
	v_mfma_f32_32x32x16_bf16 v[82:97], v[216:219], v[118:121], v[82:97]
	ds_read_b128 v[240:243], v253 offset:12960
	s_nop 1
	s_waitcnt lgkmcnt(5)
	v_mfma_f32_32x32x16_bf16 v[66:81], v[220:223], v[122:125], v[66:81]
	ds_read_b128 v[196:199], v253 offset:192
	v_addc_co_u32_e32 v245, vcc, 0, v245, vcc
	s_waitcnt lgkmcnt(5)
	v_mfma_f32_32x32x16_bf16 v[82:97], v[224:227], v[122:125], v[82:97]
	ds_read_b128 v[200:203], v253 offset:12992
	global_load_dwordx4 v[98:101], v[246:247], off
	s_waitcnt lgkmcnt(5)
	v_mfma_f32_32x32x16_bf16 v[66:81], v[228:231], v[130:133], v[66:81]
	ds_read_b128 v[204:207], v253 offset:224
	global_load_dwordx4 v[102:105], v[244:245], off
	s_waitcnt lgkmcnt(5)
	v_mfma_f32_32x32x16_bf16 v[82:97], v[232:235], v[130:133], v[82:97]
	ds_read_b128 v[208:211], v253 offset:13024
	v_lshl_add_u64 v[246:247], s[2:3], 0, v[178:179]
	s_waitcnt lgkmcnt(5)
	v_mfma_f32_32x32x16_bf16 v[66:81], v[236:239], v[134:137], v[66:81]
	ds_read_b128 v[212:215], v253 offset:256
	v_add_co_u32_e32 v248, vcc, 0x1a000000, v246
	s_waitcnt lgkmcnt(5)
	v_mfma_f32_32x32x16_bf16 v[82:97], v[240:243], v[134:137], v[82:97]
	ds_read_b128 v[216:219], v253 offset:13056
	v_lshl_add_u64 v[244:245], s[2:3], 0, v[174:175]
	s_waitcnt lgkmcnt(5)
	v_mfma_f32_32x32x16_bf16 v[66:81], v[196:199], v[138:141], v[66:81]
	ds_read_b128 v[220:223], v253 offset:288
	s_nop 0
	s_waitcnt lgkmcnt(5)
	v_mfma_f32_32x32x16_bf16 v[82:97], v[200:203], v[138:141], v[82:97]
	ds_read_b128 v[224:227], v253 offset:13088
	v_addc_co_u32_e32 v249, vcc, 0, v247, vcc
	s_waitcnt lgkmcnt(5)
	v_mfma_f32_32x32x16_bf16 v[66:81], v[204:207], v[142:145], v[66:81]
	ds_read_b128 v[228:231], v253 offset:320
	global_load_dwordx4 v[106:109], v[244:245], off
	s_waitcnt lgkmcnt(5)
	v_mfma_f32_32x32x16_bf16 v[82:97], v[208:211], v[142:145], v[82:97]
	ds_read_b128 v[232:235], v253 offset:13120
	global_load_dwordx4 v[126:129], v[248:249], off offset:128
	s_waitcnt lgkmcnt(5)
	v_mfma_f32_32x32x16_bf16 v[66:81], v[212:215], v[146:149], v[66:81]
	ds_read_b128 v[236:239], v253 offset:352
	v_add_co_u32_e32 v244, vcc, 0x1a400000, v246
	s_waitcnt lgkmcnt(5)
	v_mfma_f32_32x32x16_bf16 v[82:97], v[216:219], v[146:149], v[82:97]
	ds_read_b128 v[240:243], v253 offset:13152
	s_nop 1
	s_waitcnt lgkmcnt(5)
	v_mfma_f32_32x32x16_bf16 v[66:81], v[220:223], v[154:157], v[66:81]
	v_addc_co_u32_e32 v245, vcc, 0, v247, vcc
	s_waitcnt lgkmcnt(4)
	v_mfma_f32_32x32x16_bf16 v[82:97], v[224:227], v[154:157], v[82:97]
	global_load_dwordx4 v[150:153], v[244:245], off offset:128
	s_waitcnt lgkmcnt(3)
	v_mfma_f32_32x32x16_bf16 v[66:81], v[228:231], v[158:161], v[66:81]
	s_waitcnt lgkmcnt(2)
	v_mfma_f32_32x32x16_bf16 v[82:97], v[232:235], v[158:161], v[82:97]
	s_waitcnt lgkmcnt(1)
	v_mfma_f32_32x32x16_bf16 v[66:81], v[236:239], v[162:165], v[66:81]
	s_waitcnt lgkmcnt(0)
	v_mfma_f32_32x32x16_bf16 v[82:97], v[240:243], v[162:165], v[82:97]
	ds_read_b128 v[196:199], v252 offset:25600
	ds_read_b128 v[200:203], v252 offset:30208
	ds_read_b128 v[204:207], v252 offset:34816
	ds_read_b128 v[208:211], v252 offset:39424
	ds_read_b128 v[212:215], v252 offset:25632
	ds_read_b128 v[216:219], v252 offset:30240
	s_setprio 0
	s_add_i32 s26, s37, 63
	s_cmp_le_i32 s26, s30
	s_cbranch_scc1 .LaF2_1
	v_add_u32_e32 v0, s37, v168
	v_add_u32_e32 v184, 32, v0
	v_cmp_le_i32_e32 vcc, v184, v173
	v_add_u32_e32 v184, 33, v0
	s_nop 3
	v_cndmask_b32_e32 v82, v180, v82, vcc
	v_cmp_lt_i32_e32 vcc, v0, v173
	s_nop 1
	v_cndmask_b32_e32 v67, v180, v67, vcc
	v_cmp_le_i32_e32 vcc, v0, v173
	s_nop 1
	v_cndmask_b32_e32 v66, v180, v66, vcc
	v_cmp_le_i32_e32 vcc, v184, v173
	v_add_u32_e32 v184, 2, v0
	s_nop 0
	v_cndmask_b32_e32 v83, v180, v83, vcc
	v_cmp_le_i32_e32 vcc, v184, v173
	v_add_u32_e32 v184, 34, v0
	s_nop 0
	v_cndmask_b32_e32 v68, v180, v68, vcc
	v_cmp_le_i32_e32 vcc, v184, v173
	v_add_u32_e32 v184, 3, v0
	s_nop 0
	v_cndmask_b32_e32 v84, v180, v84, vcc
	v_cmp_le_i32_e32 vcc, v184, v173
	v_add_u32_e32 v184, 35, v0
	s_nop 0
	v_cndmask_b32_e32 v69, v180, v69, vcc
	v_cmp_le_i32_e32 vcc, v184, v173
	v_add_u32_e32 v184, 4, v0
	s_nop 0
	v_cndmask_b32_e32 v85, v180, v85, vcc
	v_cmp_le_i32_e32 vcc, v184, v173
	v_add_u32_e32 v184, 36, v0
	s_nop 0
	v_cndmask_b32_e32 v70, v180, v70, vcc
	v_cmp_le_i32_e32 vcc, v184, v173
	v_add_u32_e32 v184, 5, v0
	s_nop 0
	v_cndmask_b32_e32 v86, v180, v86, vcc
	v_cmp_le_i32_e32 vcc, v184, v173
	v_add_u32_e32 v184, 37, v0
	s_nop 0
	v_cndmask_b32_e32 v71, v180, v71, vcc
	v_cmp_le_i32_e32 vcc, v184, v173
	v_add_u32_e32 v184, 6, v0
	s_nop 0
	v_cndmask_b32_e32 v87, v180, v87, vcc
	v_cmp_le_i32_e32 vcc, v184, v173
	v_add_u32_e32 v184, 38, v0
	s_nop 0
	v_cndmask_b32_e32 v72, v180, v72, vcc
	v_cmp_le_i32_e32 vcc, v184, v173
	v_add_u32_e32 v184, 7, v0
	s_nop 0
	v_cndmask_b32_e32 v88, v180, v88, vcc
	v_cmp_le_i32_e32 vcc, v184, v173
	v_add_u32_e32 v184, 39, v0
	s_nop 0
	v_cndmask_b32_e32 v73, v180, v73, vcc
	v_cmp_le_i32_e32 vcc, v184, v173
	v_add_u32_e32 v184, 16, v0
	s_nop 0
	v_cndmask_b32_e32 v89, v180, v89, vcc
	v_cmp_le_i32_e32 vcc, v184, v173
	v_add_u32_e32 v184, 48, v0
	s_nop 0
	v_cndmask_b32_e32 v74, v180, v74, vcc
	v_cmp_le_i32_e32 vcc, v184, v173
	v_add_u32_e32 v184, 17, v0
	s_nop 0
	v_cndmask_b32_e32 v90, v180, v90, vcc
	v_cmp_le_i32_e32 vcc, v184, v173
	v_add_u32_e32 v184, 49, v0
	s_nop 0
	v_cndmask_b32_e32 v75, v180, v75, vcc
	v_cmp_le_i32_e32 vcc, v184, v173
	v_add_u32_e32 v184, 18, v0
	s_nop 0
	v_cndmask_b32_e32 v91, v180, v91, vcc
	v_cmp_le_i32_e32 vcc, v184, v173
	v_add_u32_e32 v184, 50, v0
	s_nop 0
	v_cndmask_b32_e32 v76, v180, v76, vcc
	v_cmp_le_i32_e32 vcc, v184, v173
	v_add_u32_e32 v184, 19, v0
	s_nop 0
	v_cndmask_b32_e32 v92, v180, v92, vcc
	v_cmp_le_i32_e32 vcc, v184, v173
	v_add_u32_e32 v184, 51, v0
	s_nop 0
	v_cndmask_b32_e32 v77, v180, v77, vcc
	v_cmp_le_i32_e32 vcc, v184, v173
	v_add_u32_e32 v184, 20, v0
	s_nop 0
	v_cndmask_b32_e32 v93, v180, v93, vcc
	v_cmp_le_i32_e32 vcc, v184, v173
	v_add_u32_e32 v184, 52, v0
	s_nop 0
	v_cndmask_b32_e32 v78, v180, v78, vcc
	v_cmp_le_i32_e32 vcc, v184, v173
	v_add_u32_e32 v184, 21, v0
	s_nop 0
	v_cndmask_b32_e32 v94, v180, v94, vcc
	v_cmp_le_i32_e32 vcc, v184, v173
	v_add_u32_e32 v184, 53, v0
	s_nop 0
	v_cndmask_b32_e32 v79, v180, v79, vcc
	v_cmp_le_i32_e32 vcc, v184, v173
	v_add_u32_e32 v184, 22, v0
	s_nop 0
	v_cndmask_b32_e32 v95, v180, v95, vcc
	v_cmp_le_i32_e32 vcc, v184, v173
	v_add_u32_e32 v184, 54, v0
	s_nop 0
	v_cndmask_b32_e32 v80, v180, v80, vcc
	v_cmp_le_i32_e32 vcc, v184, v173
	v_add_u32_e32 v184, 23, v0
	v_add_u32_e32 v0, 55, v0
	v_cndmask_b32_e32 v96, v180, v96, vcc
	v_cmp_le_i32_e32 vcc, v184, v173
	s_nop 1
	v_cndmask_b32_e32 v81, v180, v81, vcc
	v_cmp_le_i32_e32 vcc, v0, v173
	s_nop 1
	v_cndmask_b32_e32 v97, v180, v97, vcc

.LaF2_2:
	v_sub_f32_e32 v66, v66, v183
	v_sub_f32_e32 v67, v67, v183
	v_sub_f32_e32 v68, v68, v183
	v_sub_f32_e32 v69, v69, v183
	v_sub_f32_e32 v70, v70, v183
	v_sub_f32_e32 v71, v71, v183
	v_sub_f32_e32 v72, v72, v183
	v_sub_f32_e32 v73, v73, v183
	v_sub_f32_e32 v74, v74, v183
	v_sub_f32_e32 v75, v75, v183
	v_sub_f32_e32 v76, v76, v183
	v_sub_f32_e32 v77, v77, v183
	v_sub_f32_e32 v78, v78, v183
	v_sub_f32_e32 v79, v79, v183
	v_sub_f32_e32 v80, v80, v183
	v_sub_f32_e32 v81, v81, v183
	v_exp_f32_e32 v66, v66
	v_exp_f32_e32 v67, v67
	v_exp_f32_e32 v68, v68
	v_exp_f32_e32 v69, v69
	v_exp_f32_e32 v70, v70
	v_exp_f32_e32 v71, v71
	v_exp_f32_e32 v72, v72
	v_exp_f32_e32 v73, v73
	v_exp_f32_e32 v74, v74
	v_exp_f32_e32 v75, v75
	v_exp_f32_e32 v76, v76
	v_exp_f32_e32 v77, v77
	v_exp_f32_e32 v78, v78
	v_exp_f32_e32 v79, v79
	v_exp_f32_e32 v80, v80
	v_exp_f32_e32 v81, v81
	v_pk_add_f32 v[184:185], v[66:67], v[68:69]
	v_pk_add_f32 v[186:187], v[70:71], v[72:73]
	v_pk_add_f32 v[184:185], v[184:185], v[74:75]
	v_pk_add_f32 v[186:187], v[186:187], v[76:77]
	v_pk_add_f32 v[184:185], v[184:185], v[78:79]
	v_pk_add_f32 v[186:187], v[186:187], v[80:81]
	v_cvt_pk_bf16_f32 v66, v66, v67
	v_cvt_pk_bf16_f32 v67, v68, v69
	v_cvt_pk_bf16_f32 v68, v70, v71
	v_cvt_pk_bf16_f32 v69, v72, v73
	v_cvt_pk_bf16_f32 v70, v74, v75
	v_cvt_pk_bf16_f32 v71, v76, v77
	v_cvt_pk_bf16_f32 v72, v78, v79
	v_cvt_pk_bf16_f32 v73, v80, v81
	s_nop 1
	s_setprio 1
	s_waitcnt lgkmcnt(5)
	v_mfma_f32_32x32x16_bf16 v[50:65], v[196:199], v[66:69], v[50:65]
	ds_read_b128 v[220:223], v252 offset:34848
	v_sub_f32_e32 v82, v82, v183
	v_sub_f32_e32 v83, v83, v183
	v_sub_f32_e32 v84, v84, v183
	v_sub_f32_e32 v85, v85, v183
	v_sub_f32_e32 v86, v86, v183
	v_sub_f32_e32 v87, v87, v183
	v_sub_f32_e32 v88, v88, v183
	s_waitcnt lgkmcnt(5)
	v_mfma_f32_32x32x16_bf16 v[34:49], v[200:203], v[66:69], v[34:49]
	ds_read_b128 v[224:227], v252 offset:39456
	v_sub_f32_e32 v89, v89, v183
	v_sub_f32_e32 v90, v90, v183
	v_sub_f32_e32 v91, v91, v183
	v_sub_f32_e32 v92, v92, v183
	v_sub_f32_e32 v93, v93, v183
	v_sub_f32_e32 v94, v94, v183
	v_sub_f32_e32 v95, v95, v183
	s_waitcnt lgkmcnt(5)
	v_mfma_f32_32x32x16_bf16 v[18:33], v[204:207], v[66:69], v[18:33]
	ds_read_b128 v[228:231], v252 offset:25664
	v_sub_f32_e32 v96, v96, v183
	v_sub_f32_e32 v97, v97, v183
	v_exp_f32_e32 v82, v82
	v_exp_f32_e32 v83, v83
	v_exp_f32_e32 v84, v84
	v_exp_f32_e32 v85, v85
	v_exp_f32_e32 v86, v86
	s_waitcnt lgkmcnt(5)
	v_mfma_f32_32x32x16_bf16 v[2:17], v[208:211], v[66:69], v[2:17]
	ds_read_b128 v[232:235], v252 offset:30272
	v_exp_f32_e32 v87, v87
	v_exp_f32_e32 v88, v88
	v_exp_f32_e32 v89, v89
	v_exp_f32_e32 v90, v90
	v_exp_f32_e32 v91, v91
	v_exp_f32_e32 v92, v92
	v_exp_f32_e32 v93, v93
	s_waitcnt lgkmcnt(5)
	v_mfma_f32_32x32x16_bf16 v[50:65], v[212:215], v[70:73], v[50:65]
	ds_read_b128 v[236:239], v252 offset:34880
	v_exp_f32_e32 v94, v94
	v_exp_f32_e32 v95, v95
	v_exp_f32_e32 v96, v96
	v_exp_f32_e32 v97, v97
	v_pk_add_f32 v[184:185], v[184:185], v[82:83]
	v_pk_add_f32 v[186:187], v[186:187], v[84:85]
	v_pk_add_f32 v[184:185], v[184:185], v[86:87]
	s_waitcnt lgkmcnt(5)
	v_mfma_f32_32x32x16_bf16 v[34:49], v[216:219], v[70:73], v[34:49]
	ds_read_b128 v[240:243], v252 offset:39488
	v_pk_add_f32 v[186:187], v[186:187], v[88:89]
	v_pk_add_f32 v[184:185], v[184:185], v[90:91]
	v_pk_add_f32 v[186:187], v[186:187], v[92:93]
	v_pk_add_f32 v[184:185], v[184:185], v[94:95]
	v_pk_add_f32 v[186:187], v[186:187], v[96:97]
	v_pk_add_f32 v[184:185], v[184:185], v[186:187]
	v_cvt_pk_bf16_f32 v74, v82, v83
	s_waitcnt lgkmcnt(5)
	v_mfma_f32_32x32x16_bf16 v[18:33], v[220:223], v[70:73], v[18:33]
	ds_read_b128 v[196:199], v252 offset:25696
	v_cvt_pk_bf16_f32 v75, v84, v85
	v_cvt_pk_bf16_f32 v76, v86, v87
	v_cvt_pk_bf16_f32 v77, v88, v89
	v_cvt_pk_bf16_f32 v78, v90, v91
	v_cvt_pk_bf16_f32 v79, v92, v93
	v_cvt_pk_bf16_f32 v80, v94, v95
	v_cvt_pk_bf16_f32 v81, v96, v97
	s_waitcnt lgkmcnt(5)
	v_mfma_f32_32x32x16_bf16 v[2:17], v[224:227], v[70:73], v[2:17]
	ds_read_b128 v[200:203], v252 offset:30304
	v_add_f32_e32 v184, v184, v185
	v_add_f32_e32 v182, v182, v184
	s_waitcnt lgkmcnt(5)
	v_mfma_f32_32x32x16_bf16 v[50:65], v[228:231], v[74:77], v[50:65]
	ds_read_b128 v[204:207], v252 offset:34912
	s_bitcmp1_b32 s36, 0
	s_cselect_b32 s99, 0xac00, 0
	s_waitcnt lgkmcnt(5)
	v_mfma_f32_32x32x16_bf16 v[34:49], v[232:235], v[74:77], v[34:49]
	ds_read_b128 v[208:211], v252 offset:39520
	s_add_i32 s99, s99, 0
	v_add_u32_e32 v250, s99, v170
	s_waitcnt lgkmcnt(5)
	v_mfma_f32_32x32x16_bf16 v[18:33], v[236:239], v[74:77], v[18:33]
	s_waitcnt vmcnt(4)
	ds_write_b128 v250, v[98:101]
	s_waitcnt lgkmcnt(5)
	v_mfma_f32_32x32x16_bf16 v[2:17], v[240:243], v[74:77], v[2:17]
	s_waitcnt vmcnt(3)
	ds_write_b128 v250, v[102:105] offset:12800
	s_waitcnt lgkmcnt(5)
	v_mfma_f32_32x32x16_bf16 v[50:65], v[196:199], v[78:81], v[50:65]
	v_add_u32_e32 v250, s99, v172
	s_waitcnt vmcnt(2)
	s_waitcnt lgkmcnt(4)
	v_mfma_f32_32x32x16_bf16 v[34:49], v[200:203], v[78:81], v[34:49]
	ds_write_b128 v250, v[106:109] offset:256
	v_add_u32_e32 v250, s99, v169
	s_waitcnt lgkmcnt(4)
	v_mfma_f32_32x32x16_bf16 v[18:33], v[204:207], v[78:81], v[18:33]
	s_waitcnt vmcnt(1)
	ds_write_b128 v250, v[126:129] offset:25600
	s_waitcnt lgkmcnt(4)
	v_mfma_f32_32x32x16_bf16 v[2:17], v[208:211], v[78:81], v[2:17]
	s_waitcnt vmcnt(0)
	ds_write_b128 v250, v[150:153] offset:34816
	s_setprio 0
	s_branch .LBB0_1490
